# EpiQ: ssq loads hoisted; fused-LN epilogue: cache-warming byte loads for the residual rows
# baseline (speedup 1.0000x reference)
; __device__ __forceinline__ float sumsq4(f32x4 x) { return (x[0] * x[0] + x[1] * x[1]) + (x[2] * x[2] + x[3] * x[3]); }
;     __device__ __forceinline__ void fused(AccT& acc, const Unit& u, int wr, int wc, int fr, int fq, LAS unsigned char* lx, int tid) const {
;     ...
; #pragma unroll
;         for (int ai = 0; ai < 2; ++ai)
; #pragma unroll
;             for (int m = 0; m < 4; ++m) {
;                 const int row = EPI_ROW(u, ai, m); float s1 = 0.f, s2 = 0.f;
; #pragma unroll
;                 for (int bj = 0; bj < 2; ++bj) {
;                     const half8 rv = *(const half8*)(res + (size_t)row * DM + EPI_COL(u, bj));
; #pragma unroll
;                     for (int e = 0; e < 4; ++e) { acc[ai][bj][m][0][e] += ALPHA * (float)rv[e]; acc[ai][bj][m][1][e] += ALPHA * (float)rv[4 + e]; }
;                     const f32x4 a0 = acc[ai][bj][m][0], a1 = acc[ai][bj][m][1];
;                     s1 += ((a0[0] + a0[1]) + (a0[2] + a0[3])) + ((a1[0] + a1[1]) + (a1[2] + a1[3])); s2 += sumsq4(a0) + sumsq4(a1);
;                 }
;                 s1 += __shfl_xor(s1, 16); s1 += __shfl_xor(s1, 32); s2 += __shfl_xor(s2, 16); s2 += __shfl_xor(s2, 32);
;                 if (fq == 0) P[(ai * 128 + wr * 64 + m * 16 + fr) * 4 + wc] = (f32x2){s1, s2};
.LBB0_86:
	v_mov_b32_e32 v239, v216
	s_lshl_b32 s10, s61, 8
	v_ashrrev_i32_e32 v140, 2, v239
	v_and_b32_e32 v238, 0xffffffc0, v140
	v_bfe_u32 v141, v239, 6, 2
	v_and_b32_e32 v229, 15, v239
	v_bfe_u32 v142, v239, 4, 2
	v_add_u32_e32 v140, s10, v238
	v_or_b32_e32 v158, v140, v229
	s_lshl_b32 s0, s16, 8
	v_lshlrev_b32_e32 v140, 5, v141
	v_lshlrev_b32_e32 v143, 3, v142
	v_and_b32_e32 v144, 64, v237
	v_or3_b32 v140, v140, s0, v143
	v_xor_b32_e32 v143, 16, v237
	v_add_u32_e32 v144, 64, v144
	v_cmp_lt_i32_e32 vcc, v143, v144
	v_readlane_b32 s0, v253, 5
	v_ashrrev_i32_e32 v159, 31, v158
	v_cndmask_b32_e32 v143, v237, v143, vcc
	v_lshlrev_b32_e32 v241, 2, v143
	v_xor_b32_e32 v143, 32, v237
	v_cmp_lt_i32_e32 vcc, v143, v144
	v_lshl_add_u32 v154, v141, 3, s0
	v_readlane_b32 s0, v255, 2
	v_cndmask_b32_e32 v143, v237, v143, vcc
	v_lshlrev_b32_e32 v240, 2, v143
	v_cmp_eq_u32_e32 vcc, 0, v142
	v_lshlrev_b64 v[142:143], 11, v[158:159]
	v_readlane_b32 s1, v255, 3
	v_ashrrev_i32_e32 v141, 31, v140
	v_mov_b32_e32 v166, v118
	v_lshl_add_u64 v[144:145], s[0:1], 0, v[142:143]
	v_lshl_add_u64 v[144:145], v[140:141], 1, v[144:145]
	flat_load_dwordx4 v[148:151], v[144:145]
	flat_load_dwordx4 v[162:165], v[144:145] offset:256
	v_mov_b32_e32 v244, 0x8000
	v_mov_b32_e32 v245, 0
	v_lshl_add_u64 v[246:247], v[144:145], 0, v[244:245]
	v_lshl_add_u64 v[248:249], v[246:247], 0, v[244:245]
	v_lshl_add_u64 v[250:251], v[248:249], 0, v[244:245]
	flat_load_ubyte v242, v[246:247]
	flat_load_ubyte v242, v[246:247] offset:256
	flat_load_ubyte v242, v[248:249]
	flat_load_ubyte v242, v[248:249] offset:256
	flat_load_ubyte v242, v[250:251]
	flat_load_ubyte v242, v[250:251] offset:256
	v_mov_b32_e32 v244, 0x40000
	v_lshl_add_u64 v[246:247], v[144:145], 0, v[244:245]
	v_mov_b32_e32 v244, 0x8000
	v_lshl_add_u64 v[248:249], v[246:247], 0, v[244:245]
	flat_load_ubyte v242, v[246:247]
	flat_load_ubyte v242, v[246:247] offset:256
	v_lshl_add_u64 v[250:251], v[248:249], 0, v[244:245]
	flat_load_ubyte v242, v[248:249]
	flat_load_ubyte v242, v[248:249] offset:256
	v_lshl_add_u64 v[246:247], v[250:251], 0, v[244:245]
	flat_load_ubyte v242, v[250:251]
	flat_load_ubyte v242, v[250:251] offset:256
	flat_load_ubyte v242, v[246:247]
	flat_load_ubyte v242, v[246:247] offset:256
	s_mov_b32 s0, 0x3fd744fd
	v_pk_mov_b32 v[118:119], v[118:119], v[116:117] op_sel:[1,0]
	v_mov_b32_e32 v167, v116
	v_mov_b32_e32 v116, v120
	v_or_b32_e32 v155, v238, v229
	s_waitcnt vmcnt(0) lgkmcnt(0)
	v_cvt_f32_f16_sdwa v156, v148 dst_sel:DWORD dst_unused:UNUSED_PAD src0_sel:WORD_1
	v_cvt_f32_f16_e32 v144, v164
	v_cvt_f32_f16_sdwa v145, v164 dst_sel:DWORD dst_unused:UNUSED_PAD src0_sel:WORD_1
	v_cvt_f32_f16_sdwa v164, v150 dst_sel:DWORD dst_unused:UNUSED_PAD src0_sel:WORD_1
	v_pk_fma_f32 v[126:127], v[144:145], s[0:1], v[126:127] op_sel_hi:[1,0,1]
	v_cvt_f32_f16_e32 v144, v165
	v_cvt_f32_f16_sdwa v145, v165 dst_sel:DWORD dst_unused:UNUSED_PAD src0_sel:WORD_1
	v_mov_b32_e32 v146, v127
	v_pk_fma_f32 v[128:129], v[144:145], s[0:1], v[128:129] op_sel_hi:[1,0,1]
	s_nop 0
	v_mov_b32_e32 v147, v129
	v_mov_b32_e32 v144, v126
	v_mov_b32_e32 v145, v128
	v_pk_mul_f32 v[146:147], v[146:147], v[146:147]
	s_nop 0
	v_pk_fma_f32 v[144:145], v[144:145], v[144:145], v[146:147]
	v_mov_b32_e32 v146, v122
	v_pk_add_f32 v[152:153], v[144:145], v[144:145] op_sel_hi:[0,1]
	v_cvt_f32_f16_e32 v145, v162
	v_cvt_f32_f16_e32 v144, v148
	v_mov_b32_e32 v147, v114
	v_pk_mov_b32 v[122:123], v[122:123], v[114:115] op_sel:[1,0]
	v_mov_b32_e32 v157, v145
	v_pk_fma_f32 v[144:145], v[144:145], s[0:1], v[146:147] op_sel_hi:[1,0,1]
	v_cvt_f32_f16_e32 v147, v163
	v_pk_fma_f32 v[122:123], v[156:157], s[0:1], v[122:123] op_sel_hi:[1,0,1]
	v_cvt_f32_f16_e32 v156, v149
	v_cvt_f32_f16_sdwa v157, v162 dst_sel:DWORD dst_unused:UNUSED_PAD src0_sel:WORD_1
	v_mov_b32_e32 v165, v147
	v_mov_b32_e32 v114, v124
	v_pk_fma_f32 v[118:119], v[164:165], s[0:1], v[118:119] op_sel_hi:[1,0,1]
	v_cvt_f32_f16_sdwa v164, v149 dst_sel:DWORD dst_unused:UNUSED_PAD src0_sel:WORD_1
	v_mov_b32_e32 v165, v157
	v_pk_fma_f32 v[148:149], v[156:157], s[0:1], v[114:115] op_sel_hi:[1,0,1]
	v_cvt_f32_f16_e32 v156, v151
	v_cvt_f32_f16_sdwa v157, v163 dst_sel:DWORD dst_unused:UNUSED_PAD src0_sel:WORD_1
	v_cvt_f32_f16_e32 v146, v150
	v_cvt_f32_f16_sdwa v162, v151 dst_sel:DWORD dst_unused:UNUSED_PAD src0_sel:WORD_1
	v_mov_b32_e32 v114, v125
	v_mov_b32_e32 v163, v157
	v_pk_fma_f32 v[150:151], v[156:157], s[0:1], v[116:117] op_sel_hi:[1,0,1]
	v_pk_fma_f32 v[114:115], v[164:165], s[0:1], v[114:115] op_sel_hi:[1,0,1]
	v_mov_b32_e32 v116, v121
	v_pk_mul_f32 v[120:121], v[144:145], v[144:145]
	v_pk_mul_f32 v[124:125], v[122:123], v[122:123]
	v_pk_fma_f32 v[146:147], v[146:147], s[0:1], v[166:167] op_sel_hi:[1,0,1]
	v_pk_fma_f32 v[116:117], v[162:163], s[0:1], v[116:117] op_sel_hi:[1,0,1]
	v_pk_mul_f32 v[156:157], v[148:149], v[148:149]
	v_pk_mul_f32 v[162:163], v[114:115], v[114:115]
	v_pk_mov_b32 v[120:121], v[144:145], v[120:121] op_sel:[1,0]
	v_pk_mov_b32 v[124:125], v[148:149], v[124:125] op_sel:[1,0]
	v_pk_mul_f32 v[164:165], v[146:147], v[146:147]
	v_pk_add_f32 v[120:121], v[120:121], v[124:125]
	v_pk_mov_b32 v[124:125], v[146:147], v[156:157] op_sel:[1,0]
	v_pk_mov_b32 v[156:157], v[150:151], v[162:163] op_sel:[1,0]
	v_pk_mul_f32 v[166:167], v[118:119], v[118:119]
	v_pk_add_f32 v[124:125], v[124:125], v[156:157]
	v_pk_mul_f32 v[168:169], v[150:151], v[150:151]
	v_pk_mul_f32 v[170:171], v[116:117], v[116:117]
	v_pk_add_f32 v[120:121], v[120:121], v[124:125]
	v_mov_b32_e32 v124, v126
	v_mov_b32_e32 v125, v164
	v_pk_mov_b32 v[156:157], v[126:127], v[166:167] op_sel:[1,0]
	v_pk_mov_b32 v[162:163], v[128:129], v[170:171] op_sel:[1,0]
	v_pk_add_f32 v[124:125], v[124:125], v[156:157]
	v_mov_b32_e32 v156, v128
	v_mov_b32_e32 v157, v168
	v_pk_add_f32 v[156:157], v[156:157], v[162:163]
	v_pk_mul_f32 v[162:163], v[148:149], v[114:115]
	v_pk_add_f32 v[124:125], v[124:125], v[156:157]
	v_pk_mul_f32 v[156:157], v[144:145], v[122:123]
	v_pk_add_f32 v[120:121], v[120:121], v[124:125]
	v_pk_add_f32 v[124:125], v[144:145], v[122:123]
	v_pk_mul_f32 v[164:165], v[150:151], v[116:117]
	v_mov_b32_e32 v125, v157
	v_pk_add_f32 v[156:157], v[148:149], v[114:115]
	v_mov_b32_e32 v152, v1
	v_mov_b32_e32 v157, v163
	v_pk_add_f32 v[124:125], v[124:125], v[156:157]
	v_pk_add_f32 v[156:157], v[146:147], v[118:119]
	v_pk_mul_f32 v[162:163], v[146:147], v[118:119]
	v_lshl_add_u32 v115, v155, 5, v154
	v_mov_b32_e32 v157, v163
	v_pk_add_f32 v[162:163], v[150:151], v[116:117]
	s_nop 0
	v_mov_b32_e32 v163, v165
	v_pk_add_f32 v[156:157], v[156:157], v[162:163]
	s_nop 0
	v_pk_add_f32 v[124:125], v[124:125], v[156:157]
	s_nop 0
	v_pk_add_f32 v[124:125], v[124:125], v[152:153]
	s_nop 0
	v_pk_add_f32 v[120:121], v[120:121], v[124:125]
	ds_bpermute_b32 v124, v241, v120
	ds_bpermute_b32 v125, v241, v121
	s_waitcnt lgkmcnt(0)
	v_pk_add_f32 v[120:121], v[120:121], v[124:125]
	ds_bpermute_b32 v124, v240, v120
	ds_bpermute_b32 v125, v240, v121
	s_and_saveexec_b64 s[0:1], vcc
	s_cbranch_execz .LBB0_88
;     __device__ __forceinline__ void fused(AccT& acc, const Unit& u, int wr, int wc, int fr, int fq, LAS unsigned char* lx, int tid) const {
;     ...
;                 s1 += __shfl_xor(s1, 16); s1 += __shfl_xor(s1, 32); s2 += __shfl_xor(s2, 16); s2 += __shfl_xor(s2, 32);
;                 if (fq == 0) P[(ai * 128 + wr * 64 + m * 16 + fr) * 4 + wc] = (f32x2){s1, s2};
	s_waitcnt lgkmcnt(0)
	v_pk_add_f32 v[120:121], v[120:121], v[124:125]
	ds_write_b64 v115, v[120:121]

; __device__ __forceinline__ float sumsq4(f32x4 x) { return (x[0] * x[0] + x[1] * x[1]) + (x[2] * x[2] + x[3] * x[3]); }
;     __device__ __forceinline__ void fused(AccT& acc, const Unit& u, int wr, int wc, int fr, int fq, LAS unsigned char* lx, int tid) const {
;     ...
; #pragma unroll
;         for (int ai = 0; ai < 2; ++ai)
; #pragma unroll
;             for (int m = 0; m < 4; ++m) {
;                 const int row = EPI_ROW(u, ai, m); float s1 = 0.f, s2 = 0.f;
; #pragma unroll
;                 for (int bj = 0; bj < 2; ++bj) {
;                     const half8 rv = *(const half8*)(res + (size_t)row * DM + EPI_COL(u, bj));
; #pragma unroll
;                     for (int e = 0; e < 4; ++e) { acc[ai][bj][m][0][e] += ALPHA * (float)rv[e]; acc[ai][bj][m][1][e] += ALPHA * (float)rv[4 + e]; }
;                     const f32x4 a0 = acc[ai][bj][m][0], a1 = acc[ai][bj][m][1];
;                     s1 += ((a0[0] + a0[1]) + (a0[2] + a0[3])) + ((a1[0] + a1[1]) + (a1[2] + a1[3])); s2 += sumsq4(a0) + sumsq4(a1);
;                 }
;                 s1 += __shfl_xor(s1, 16); s1 += __shfl_xor(s1, 32); s2 += __shfl_xor(s2, 16); s2 += __shfl_xor(s2, 32);
;                 if (fq == 0) P[(ai * 128 + wr * 64 + m * 16 + fr) * 4 + wc] = (f32x2){s1, s2};
.LBB0_161:
	v_mov_b32_e32 v239, v216
	s_lshl_b32 s0, s10, 8
	v_bfe_u32 v141, v239, 6, 2
	v_bfe_u32 v143, v239, 4, 2
	v_lshlrev_b32_e32 v142, 5, v141
	v_lshlrev_b32_e32 v144, 3, v143
	v_and_b32_e32 v145, 64, v237
	v_or3_b32 v142, v142, s0, v144
	v_xor_b32_e32 v144, 16, v237
	v_add_u32_e32 v145, 64, v145
	v_ashrrev_i32_e32 v140, 2, v239
	v_cmp_lt_i32_e32 vcc, v144, v145
	s_lshl_b32 s11, s53, 8
	v_and_b32_e32 v238, 0xffffffc0, v140
	v_cndmask_b32_e32 v144, v237, v144, vcc
	v_and_b32_e32 v229, 15, v239
	v_add_u32_e32 v140, s11, v238
	v_lshlrev_b32_e32 v241, 2, v144
	v_xor_b32_e32 v144, 32, v237
	v_or_b32_e32 v140, v140, v229
	v_cmp_lt_i32_e32 vcc, v144, v145
	v_readlane_b32 s0, v253, 5
	v_mov_b32_e32 v164, v118
	v_cndmask_b32_e32 v144, v237, v144, vcc
	v_lshl_add_u32 v154, v141, 3, s0
	v_ashrrev_i32_e32 v141, 31, v140
	v_readlane_b32 s0, v255, 2
	v_lshlrev_b32_e32 v240, 2, v144
	v_lshlrev_b64 v[144:145], 11, v[140:141]
	v_readlane_b32 s1, v255, 3
	v_cmp_eq_u32_e32 vcc, 0, v143
	v_ashrrev_i32_e32 v143, 31, v142
	v_lshl_add_u64 v[144:145], s[0:1], 0, v[144:145]
	v_lshl_add_u64 v[144:145], v[142:143], 1, v[144:145]
	flat_load_dwordx4 v[148:151], v[144:145]
	flat_load_dwordx4 v[156:159], v[144:145] offset:256
	v_mov_b32_e32 v244, 0x8000
	v_mov_b32_e32 v245, 0
	v_lshl_add_u64 v[246:247], v[144:145], 0, v[244:245]
	v_lshl_add_u64 v[248:249], v[246:247], 0, v[244:245]
	v_lshl_add_u64 v[250:251], v[248:249], 0, v[244:245]
	flat_load_ubyte v242, v[246:247]
	flat_load_ubyte v242, v[246:247] offset:256
	flat_load_ubyte v242, v[248:249]
	flat_load_ubyte v242, v[248:249] offset:256
	flat_load_ubyte v242, v[250:251]
	flat_load_ubyte v242, v[250:251] offset:256
	v_mov_b32_e32 v244, 0x40000
	v_lshl_add_u64 v[246:247], v[144:145], 0, v[244:245]
	v_mov_b32_e32 v244, 0x8000
	v_lshl_add_u64 v[248:249], v[246:247], 0, v[244:245]
	flat_load_ubyte v242, v[246:247]
	flat_load_ubyte v242, v[246:247] offset:256
	v_lshl_add_u64 v[250:251], v[248:249], 0, v[244:245]
	flat_load_ubyte v242, v[248:249]
	flat_load_ubyte v242, v[248:249] offset:256
	v_lshl_add_u64 v[246:247], v[250:251], 0, v[244:245]
	flat_load_ubyte v242, v[250:251]
	flat_load_ubyte v242, v[250:251] offset:256
	flat_load_ubyte v242, v[246:247]
	flat_load_ubyte v242, v[246:247] offset:256
	s_mov_b32 s0, 0x3fd744fd
	v_pk_mov_b32 v[118:119], v[118:119], v[116:117] op_sel:[1,0]
	v_mov_b32_e32 v165, v116
	v_mov_b32_e32 v116, v120
	v_or_b32_e32 v155, v238, v229
	s_waitcnt vmcnt(0) lgkmcnt(0)
	v_cvt_f32_f16_sdwa v162, v150 dst_sel:DWORD dst_unused:UNUSED_PAD src0_sel:WORD_1
	v_cvt_f32_f16_e32 v144, v158
	v_cvt_f32_f16_sdwa v145, v158 dst_sel:DWORD dst_unused:UNUSED_PAD src0_sel:WORD_1
	v_cvt_f32_f16_sdwa v158, v148 dst_sel:DWORD dst_unused:UNUSED_PAD src0_sel:WORD_1
	v_pk_fma_f32 v[126:127], v[144:145], s[0:1], v[126:127] op_sel_hi:[1,0,1]
	v_cvt_f32_f16_e32 v144, v159
	v_cvt_f32_f16_sdwa v145, v159 dst_sel:DWORD dst_unused:UNUSED_PAD src0_sel:WORD_1
	v_mov_b32_e32 v146, v127
	v_pk_fma_f32 v[128:129], v[144:145], s[0:1], v[128:129] op_sel_hi:[1,0,1]
	s_nop 0
	v_mov_b32_e32 v147, v129
	v_mov_b32_e32 v144, v126
	v_mov_b32_e32 v145, v128
	v_pk_mul_f32 v[146:147], v[146:147], v[146:147]
	s_nop 0
	v_pk_fma_f32 v[144:145], v[144:145], v[144:145], v[146:147]
	v_mov_b32_e32 v146, v122
	v_pk_add_f32 v[152:153], v[144:145], v[144:145] op_sel_hi:[0,1]
	v_cvt_f32_f16_e32 v145, v156
	v_cvt_f32_f16_e32 v144, v148
	v_mov_b32_e32 v147, v114
	v_pk_mov_b32 v[122:123], v[122:123], v[114:115] op_sel:[1,0]
	v_mov_b32_e32 v159, v145
	v_pk_fma_f32 v[144:145], v[144:145], s[0:1], v[146:147] op_sel_hi:[1,0,1]
	v_cvt_f32_f16_e32 v147, v157
	v_pk_fma_f32 v[122:123], v[158:159], s[0:1], v[122:123] op_sel_hi:[1,0,1]
	v_cvt_f32_f16_e32 v158, v149
	v_cvt_f32_f16_sdwa v159, v156 dst_sel:DWORD dst_unused:UNUSED_PAD src0_sel:WORD_1
	v_mov_b32_e32 v163, v147
	v_pk_fma_f32 v[118:119], v[162:163], s[0:1], v[118:119] op_sel_hi:[1,0,1]
	v_cvt_f32_f16_sdwa v162, v149 dst_sel:DWORD dst_unused:UNUSED_PAD src0_sel:WORD_1
	v_mov_b32_e32 v114, v124
	v_cvt_f32_f16_e32 v156, v151
	v_cvt_f32_f16_sdwa v157, v157 dst_sel:DWORD dst_unused:UNUSED_PAD src0_sel:WORD_1
	v_cvt_f32_f16_e32 v146, v150
	v_pk_fma_f32 v[148:149], v[158:159], s[0:1], v[114:115] op_sel_hi:[1,0,1]
	v_cvt_f32_f16_sdwa v158, v151 dst_sel:DWORD dst_unused:UNUSED_PAD src0_sel:WORD_1
	v_mov_b32_e32 v163, v159
	v_mov_b32_e32 v114, v125
	v_mov_b32_e32 v159, v157
	v_pk_fma_f32 v[150:151], v[156:157], s[0:1], v[116:117] op_sel_hi:[1,0,1]
	v_pk_fma_f32 v[114:115], v[162:163], s[0:1], v[114:115] op_sel_hi:[1,0,1]
	v_mov_b32_e32 v116, v121
	v_pk_mul_f32 v[120:121], v[144:145], v[144:145]
	v_pk_mul_f32 v[124:125], v[122:123], v[122:123]
	v_pk_fma_f32 v[146:147], v[146:147], s[0:1], v[164:165] op_sel_hi:[1,0,1]
	v_pk_fma_f32 v[116:117], v[158:159], s[0:1], v[116:117] op_sel_hi:[1,0,1]
	v_pk_mul_f32 v[156:157], v[148:149], v[148:149]
	v_pk_mul_f32 v[158:159], v[114:115], v[114:115]
	v_pk_mov_b32 v[120:121], v[144:145], v[120:121] op_sel:[1,0]
	v_pk_mov_b32 v[124:125], v[148:149], v[124:125] op_sel:[1,0]
	v_pk_mul_f32 v[162:163], v[146:147], v[146:147]
	v_pk_add_f32 v[120:121], v[120:121], v[124:125]
	v_pk_mov_b32 v[124:125], v[146:147], v[156:157] op_sel:[1,0]
	v_pk_mov_b32 v[156:157], v[150:151], v[158:159] op_sel:[1,0]
	v_pk_mul_f32 v[164:165], v[118:119], v[118:119]
	v_pk_add_f32 v[124:125], v[124:125], v[156:157]
	v_pk_mul_f32 v[166:167], v[150:151], v[150:151]
	v_pk_mul_f32 v[168:169], v[116:117], v[116:117]
	v_pk_add_f32 v[120:121], v[120:121], v[124:125]
	v_mov_b32_e32 v124, v126
	v_mov_b32_e32 v125, v162
	v_pk_mov_b32 v[156:157], v[126:127], v[164:165] op_sel:[1,0]
	v_pk_mov_b32 v[158:159], v[128:129], v[168:169] op_sel:[1,0]
	v_pk_add_f32 v[124:125], v[124:125], v[156:157]
	v_mov_b32_e32 v156, v128
	v_mov_b32_e32 v157, v166
	v_pk_add_f32 v[156:157], v[156:157], v[158:159]
	v_pk_mul_f32 v[158:159], v[148:149], v[114:115]
	v_pk_add_f32 v[124:125], v[124:125], v[156:157]
	v_pk_mul_f32 v[156:157], v[144:145], v[122:123]
	v_pk_add_f32 v[120:121], v[120:121], v[124:125]
	v_pk_add_f32 v[124:125], v[144:145], v[122:123]
	v_pk_mul_f32 v[162:163], v[150:151], v[116:117]
	v_mov_b32_e32 v125, v157
	v_pk_add_f32 v[156:157], v[148:149], v[114:115]
	v_mov_b32_e32 v152, v1
	v_mov_b32_e32 v157, v159
	v_pk_add_f32 v[124:125], v[124:125], v[156:157]
	v_pk_add_f32 v[156:157], v[146:147], v[118:119]
	v_pk_mul_f32 v[158:159], v[146:147], v[118:119]
	v_lshl_add_u32 v115, v155, 5, v154
	v_mov_b32_e32 v157, v159
	v_pk_add_f32 v[158:159], v[150:151], v[116:117]
	s_nop 0
	v_mov_b32_e32 v159, v163
	v_pk_add_f32 v[156:157], v[156:157], v[158:159]
	s_nop 0
	v_pk_add_f32 v[124:125], v[124:125], v[156:157]
	s_nop 0
	v_pk_add_f32 v[124:125], v[124:125], v[152:153]
	s_nop 0
	v_pk_add_f32 v[120:121], v[120:121], v[124:125]
	ds_bpermute_b32 v124, v241, v120
	ds_bpermute_b32 v125, v241, v121
	s_waitcnt lgkmcnt(0)
	v_pk_add_f32 v[120:121], v[120:121], v[124:125]
	ds_bpermute_b32 v124, v240, v120
	ds_bpermute_b32 v125, v240, v121
	s_and_saveexec_b64 s[0:1], vcc
	s_cbranch_execz .LBB0_163
;     __device__ __forceinline__ void fused(AccT& acc, const Unit& u, int wr, int wc, int fr, int fq, LAS unsigned char* lx, int tid) const {
;     ...
;                 s1 += __shfl_xor(s1, 16); s1 += __shfl_xor(s1, 32); s2 += __shfl_xor(s2, 16); s2 += __shfl_xor(s2, 32);
;                 if (fq == 0) P[(ai * 128 + wr * 64 + m * 16 + fr) * 4 + wc] = (f32x2){s1, s2};
	s_waitcnt lgkmcnt(0)
	v_pk_add_f32 v[120:121], v[120:121], v[124:125]
	ds_write_b64 v115, v[120:121]

; __device__ __forceinline__ float sumsq4(f32x4 x) { return (x[0] * x[0] + x[1] * x[1]) + (x[2] * x[2] + x[3] * x[3]); }
;     __device__ __forceinline__ void fused(AccT& acc, const Unit& u, int wr, int wc, int fr, int fq, LAS unsigned char* lx, int tid) const {
;     ...
; #pragma unroll
;         for (int ai = 0; ai < 2; ++ai)
; #pragma unroll
;             for (int m = 0; m < 4; ++m) {
;                 const int row = EPI_ROW(u, ai, m); float s1 = 0.f, s2 = 0.f;
; #pragma unroll
;                 for (int bj = 0; bj < 2; ++bj) {
;                     const half8 rv = *(const half8*)(res + (size_t)row * DM + EPI_COL(u, bj));
; #pragma unroll
;                     for (int e = 0; e < 4; ++e) { acc[ai][bj][m][0][e] += ALPHA * (float)rv[e]; acc[ai][bj][m][1][e] += ALPHA * (float)rv[4 + e]; }
;                     const f32x4 a0 = acc[ai][bj][m][0], a1 = acc[ai][bj][m][1];
;                     s1 += ((a0[0] + a0[1]) + (a0[2] + a0[3])) + ((a1[0] + a1[1]) + (a1[2] + a1[3])); s2 += sumsq4(a0) + sumsq4(a1);
;                 }
;                 s1 += __shfl_xor(s1, 16); s1 += __shfl_xor(s1, 32); s2 += __shfl_xor(s2, 16); s2 += __shfl_xor(s2, 32);
;                 if (fq == 0) P[(ai * 128 + wr * 64 + m * 16 + fr) * 4 + wc] = (f32x2){s1, s2};
.LBB0_382:
	v_mov_b32_e32 v239, v216
	s_lshl_b32 s11, s16, 8
	v_ashrrev_i32_e32 v140, 2, v239
	v_and_b32_e32 v238, 0xffffffc0, v140
	v_bfe_u32 v141, v239, 6, 2
	v_and_b32_e32 v229, 15, v239
	v_bfe_u32 v142, v239, 4, 2
	v_add_u32_e32 v140, s11, v238
	v_or_b32_e32 v158, v140, v229
	s_lshl_b32 s0, s10, 8
	v_lshlrev_b32_e32 v140, 5, v141
	v_lshlrev_b32_e32 v143, 3, v142
	v_and_b32_e32 v144, 64, v237
	v_or3_b32 v140, v140, s0, v143
	v_xor_b32_e32 v143, 16, v237
	v_add_u32_e32 v144, 64, v144
	v_cmp_lt_i32_e32 vcc, v143, v144
	v_readlane_b32 s0, v253, 5
	v_ashrrev_i32_e32 v159, 31, v158
	v_cndmask_b32_e32 v143, v237, v143, vcc
	v_lshlrev_b32_e32 v241, 2, v143
	v_xor_b32_e32 v143, 32, v237
	v_cmp_lt_i32_e32 vcc, v143, v144
	v_lshl_add_u32 v154, v141, 3, s0
	v_readlane_b32 s0, v255, 0
	v_cndmask_b32_e32 v143, v237, v143, vcc
	v_lshlrev_b32_e32 v240, 2, v143
	v_cmp_eq_u32_e32 vcc, 0, v142
	v_lshlrev_b64 v[142:143], 11, v[158:159]
	v_readlane_b32 s1, v255, 1
	v_ashrrev_i32_e32 v141, 31, v140
	v_mov_b32_e32 v166, v118
	v_lshl_add_u64 v[144:145], s[0:1], 0, v[142:143]
	v_lshl_add_u64 v[144:145], v[140:141], 1, v[144:145]
	flat_load_dwordx4 v[148:151], v[144:145]
	flat_load_dwordx4 v[162:165], v[144:145] offset:256
	v_mov_b32_e32 v244, 0x8000
	v_mov_b32_e32 v245, 0
	v_lshl_add_u64 v[246:247], v[144:145], 0, v[244:245]
	v_lshl_add_u64 v[248:249], v[246:247], 0, v[244:245]
	v_lshl_add_u64 v[250:251], v[248:249], 0, v[244:245]
	flat_load_ubyte v242, v[246:247]
	flat_load_ubyte v242, v[246:247] offset:256
	flat_load_ubyte v242, v[248:249]
	flat_load_ubyte v242, v[248:249] offset:256
	flat_load_ubyte v242, v[250:251]
	flat_load_ubyte v242, v[250:251] offset:256
	v_mov_b32_e32 v244, 0x40000
	v_lshl_add_u64 v[246:247], v[144:145], 0, v[244:245]
	v_mov_b32_e32 v244, 0x8000
	v_lshl_add_u64 v[248:249], v[246:247], 0, v[244:245]
	flat_load_ubyte v242, v[246:247]
	flat_load_ubyte v242, v[246:247] offset:256
	v_lshl_add_u64 v[250:251], v[248:249], 0, v[244:245]
	flat_load_ubyte v242, v[248:249]
	flat_load_ubyte v242, v[248:249] offset:256
	v_lshl_add_u64 v[246:247], v[250:251], 0, v[244:245]
	flat_load_ubyte v242, v[250:251]
	flat_load_ubyte v242, v[250:251] offset:256
	flat_load_ubyte v242, v[246:247]
	flat_load_ubyte v242, v[246:247] offset:256
	s_mov_b32 s0, 0x3fd744fd
	v_pk_mov_b32 v[118:119], v[118:119], v[116:117] op_sel:[1,0]
	v_mov_b32_e32 v167, v116
	v_mov_b32_e32 v116, v120
	v_or_b32_e32 v155, v238, v229
	s_waitcnt vmcnt(0) lgkmcnt(0)
	v_cvt_f32_f16_sdwa v156, v148 dst_sel:DWORD dst_unused:UNUSED_PAD src0_sel:WORD_1
	v_cvt_f32_f16_e32 v144, v164
	v_cvt_f32_f16_sdwa v145, v164 dst_sel:DWORD dst_unused:UNUSED_PAD src0_sel:WORD_1
	v_cvt_f32_f16_sdwa v164, v150 dst_sel:DWORD dst_unused:UNUSED_PAD src0_sel:WORD_1
	v_pk_fma_f32 v[126:127], v[144:145], s[0:1], v[126:127] op_sel_hi:[1,0,1]
	v_cvt_f32_f16_e32 v144, v165
	v_cvt_f32_f16_sdwa v145, v165 dst_sel:DWORD dst_unused:UNUSED_PAD src0_sel:WORD_1
	v_mov_b32_e32 v146, v127
	v_pk_fma_f32 v[128:129], v[144:145], s[0:1], v[128:129] op_sel_hi:[1,0,1]
	s_nop 0
	v_mov_b32_e32 v147, v129
	v_mov_b32_e32 v144, v126
	v_mov_b32_e32 v145, v128
	v_pk_mul_f32 v[146:147], v[146:147], v[146:147]
	s_nop 0
	v_pk_fma_f32 v[144:145], v[144:145], v[144:145], v[146:147]
	v_mov_b32_e32 v146, v122
	v_pk_add_f32 v[152:153], v[144:145], v[144:145] op_sel_hi:[0,1]
	v_cvt_f32_f16_e32 v145, v162
	v_cvt_f32_f16_e32 v144, v148
	v_mov_b32_e32 v147, v114
	v_pk_mov_b32 v[122:123], v[122:123], v[114:115] op_sel:[1,0]
	v_mov_b32_e32 v157, v145
	v_pk_fma_f32 v[144:145], v[144:145], s[0:1], v[146:147] op_sel_hi:[1,0,1]
	v_cvt_f32_f16_e32 v147, v163
	v_pk_fma_f32 v[122:123], v[156:157], s[0:1], v[122:123] op_sel_hi:[1,0,1]
	v_cvt_f32_f16_e32 v156, v149
	v_cvt_f32_f16_sdwa v157, v162 dst_sel:DWORD dst_unused:UNUSED_PAD src0_sel:WORD_1
	v_mov_b32_e32 v165, v147
	v_mov_b32_e32 v114, v124
	v_pk_fma_f32 v[118:119], v[164:165], s[0:1], v[118:119] op_sel_hi:[1,0,1]
	v_cvt_f32_f16_sdwa v164, v149 dst_sel:DWORD dst_unused:UNUSED_PAD src0_sel:WORD_1
	v_mov_b32_e32 v165, v157
	v_pk_fma_f32 v[148:149], v[156:157], s[0:1], v[114:115] op_sel_hi:[1,0,1]
	v_cvt_f32_f16_e32 v156, v151
	v_cvt_f32_f16_sdwa v157, v163 dst_sel:DWORD dst_unused:UNUSED_PAD src0_sel:WORD_1
	v_cvt_f32_f16_e32 v146, v150
	v_cvt_f32_f16_sdwa v162, v151 dst_sel:DWORD dst_unused:UNUSED_PAD src0_sel:WORD_1
	v_mov_b32_e32 v114, v125
	v_mov_b32_e32 v163, v157
	v_pk_fma_f32 v[150:151], v[156:157], s[0:1], v[116:117] op_sel_hi:[1,0,1]
	v_pk_fma_f32 v[114:115], v[164:165], s[0:1], v[114:115] op_sel_hi:[1,0,1]
	v_mov_b32_e32 v116, v121
	v_pk_mul_f32 v[120:121], v[144:145], v[144:145]
	v_pk_mul_f32 v[124:125], v[122:123], v[122:123]
	v_pk_fma_f32 v[146:147], v[146:147], s[0:1], v[166:167] op_sel_hi:[1,0,1]
	v_pk_fma_f32 v[116:117], v[162:163], s[0:1], v[116:117] op_sel_hi:[1,0,1]
	v_pk_mul_f32 v[156:157], v[148:149], v[148:149]
	v_pk_mul_f32 v[162:163], v[114:115], v[114:115]
	v_pk_mov_b32 v[120:121], v[144:145], v[120:121] op_sel:[1,0]
	v_pk_mov_b32 v[124:125], v[148:149], v[124:125] op_sel:[1,0]
	v_pk_mul_f32 v[164:165], v[146:147], v[146:147]
	v_pk_add_f32 v[120:121], v[120:121], v[124:125]
	v_pk_mov_b32 v[124:125], v[146:147], v[156:157] op_sel:[1,0]
	v_pk_mov_b32 v[156:157], v[150:151], v[162:163] op_sel:[1,0]
	v_pk_mul_f32 v[166:167], v[118:119], v[118:119]
	v_pk_add_f32 v[124:125], v[124:125], v[156:157]
	v_pk_mul_f32 v[168:169], v[150:151], v[150:151]
	v_pk_mul_f32 v[170:171], v[116:117], v[116:117]
	v_pk_add_f32 v[120:121], v[120:121], v[124:125]
	v_mov_b32_e32 v124, v126
	v_mov_b32_e32 v125, v164
	v_pk_mov_b32 v[156:157], v[126:127], v[166:167] op_sel:[1,0]
	v_pk_mov_b32 v[162:163], v[128:129], v[170:171] op_sel:[1,0]
	v_pk_add_f32 v[124:125], v[124:125], v[156:157]
	v_mov_b32_e32 v156, v128
	v_mov_b32_e32 v157, v168
	v_pk_add_f32 v[156:157], v[156:157], v[162:163]
	v_pk_mul_f32 v[162:163], v[148:149], v[114:115]
	v_pk_add_f32 v[124:125], v[124:125], v[156:157]
	v_pk_mul_f32 v[156:157], v[144:145], v[122:123]
	v_pk_add_f32 v[120:121], v[120:121], v[124:125]
	v_pk_add_f32 v[124:125], v[144:145], v[122:123]
	v_pk_mul_f32 v[164:165], v[150:151], v[116:117]
	v_mov_b32_e32 v125, v157
	v_pk_add_f32 v[156:157], v[148:149], v[114:115]
	v_mov_b32_e32 v152, v1
	v_mov_b32_e32 v157, v163
	v_pk_add_f32 v[124:125], v[124:125], v[156:157]
	v_pk_add_f32 v[156:157], v[146:147], v[118:119]
	v_pk_mul_f32 v[162:163], v[146:147], v[118:119]
	v_lshl_add_u32 v115, v155, 5, v154
	v_mov_b32_e32 v157, v163
	v_pk_add_f32 v[162:163], v[150:151], v[116:117]
	s_nop 0
	v_mov_b32_e32 v163, v165
	v_pk_add_f32 v[156:157], v[156:157], v[162:163]
	s_nop 0
	v_pk_add_f32 v[124:125], v[124:125], v[156:157]
	s_nop 0
	v_pk_add_f32 v[124:125], v[124:125], v[152:153]
	s_nop 0
	v_pk_add_f32 v[120:121], v[120:121], v[124:125]
	ds_bpermute_b32 v124, v241, v120
	ds_bpermute_b32 v125, v241, v121
	s_waitcnt lgkmcnt(0)
	v_pk_add_f32 v[120:121], v[120:121], v[124:125]
	ds_bpermute_b32 v124, v240, v120
	ds_bpermute_b32 v125, v240, v121
	s_and_saveexec_b64 s[0:1], vcc
	s_cbranch_execz .LBB0_384
;     __device__ __forceinline__ void fused(AccT& acc, const Unit& u, int wr, int wc, int fr, int fq, LAS unsigned char* lx, int tid) const {
;     ...
;                 s1 += __shfl_xor(s1, 16); s1 += __shfl_xor(s1, 32); s2 += __shfl_xor(s2, 16); s2 += __shfl_xor(s2, 32);
;                 if (fq == 0) P[(ai * 128 + wr * 64 + m * 16 + fr) * 4 + wc] = (f32x2){s1, s2};
	s_waitcnt lgkmcnt(0)
	v_pk_add_f32 v[120:121], v[120:121], v[124:125]
	ds_write_b64 v115, v[120:121]

; __device__ __forceinline__ unsigned pk4_fp8(float a, float b, float c, float d) { int w = 0; w = __builtin_amdgcn_cvt_pk_fp8_f32(a, b, w, false); w = __builtin_amdgcn_cvt_pk_fp8_f32(c, d, w, true); return (unsigned)w; }
;     __device__ __forceinline__ void operator()(const AccT& acc, const Unit& u, int wr, int wc, int fr, int fq) const {
; #pragma unroll
;         for (int ai = 0; ai < 2; ++ai)
; #pragma unroll
;             for (int m = 0; m < 4; ++m) {
;                 const int row = EPI_ROW(u, ai, m);
;                 const float r = __builtin_amdgcn_rsqf(ssq_q[row] * (1.0f / 256.0f) + RMS_EPS);
;                 const int pos = posof(row);
; #pragma unroll
;                 for (int bj = 0; bj < 2; ++bj) {
;                     const int col = EPI_COL(u, bj), d = col % 192;
;                     f32x4 v0 = acc[ai][bj][m][0] * r, v1 = acc[ai][bj][m][1] * r;
;                     if (d >= 128) { const int j0 = (d - 128) >> 1;
;                         const f32x4 c4 = *(const f32x4*)(cosT + pos * 32 + j0), s4 = *(const f32x4*)(sinT + pos * 32 + j0);
;                         rope8(v0, v1, c4, s4); }
;                     u32x2 w; w.x = pk4_fp8(v0[0], v0[1], v0[2], v0[3]); w.y = pk4_fp8(v1[0], v1[1], v1[2], v1[3]);
;                     *(u32x2*)(Q + (size_t)row * LDQ + col) = w;
;                 }
.LBB0_663:
	v_mov_b32_e32 v0, v216
	s_nop 0
	v_ashrrev_i32_e32 v142, 2, v0
	v_and_b32_e32 v142, 0xffffffc0, v142
	v_lshl_add_u32 v142, s2, 8, v142
	v_and_or_b32 v144, v0, 15, v142
	v_lshrrev_b32_e32 v0, 1, v0
	v_ashrrev_i32_e32 v145, 31, v144
	v_and_b32_e32 v0, 0x78, v0
	v_lshl_add_u64 v[146:147], v[144:145], 2, s[0:1]
	v_lshl_or_b32 v142, s6, 8, v0
	flat_load_dword v244, v[146:147]
	flat_load_dword v245, v[146:147] offset:64
	flat_load_dword v246, v[146:147] offset:128
	flat_load_dword v247, v[146:147] offset:192
	flat_load_dword v248, v[146:147] offset:512
	flat_load_dword v249, v[146:147] offset:576
	flat_load_dword v250, v[146:147] offset:640
	flat_load_dword v251, v[146:147] offset:704
	v_cmp_gt_i32_e32 vcc, s63, v144
	s_movk_i32 s0, 0xc0
	s_waitcnt vmcnt(0) lgkmcnt(0)
	v_fmamk_f32 v0, v244, 0x3b800000, v236
	v_rsq_f32_e32 v148, v0
	v_lshlrev_b32_e32 v0, 5, v144
	v_and_b32_e32 v143, 0x1f9e0, v0
	v_cndmask_b32_e32 v156, v143, v0, vcc
	v_mul_hi_i32 v0, v142, s62
	v_lshrrev_b32_e32 v143, 31, v0
	v_lshrrev_b32_e32 v0, 5, v0
	v_add_u32_e32 v0, v0, v143
	v_mul_lo_u32 v0, v0, s0
	v_ashrrev_i32_e32 v157, 31, v156
	v_sub_u32_e32 v0, v142, v0
	v_pk_mul_f32 v[150:151], v[124:125], v[148:149] op_sel_hi:[1,0]
	v_cmp_lt_i32_e32 vcc, s49, v0
	v_add_u32_e32 v0, 0xffffff80, v0
	v_lshlrev_b64 v[124:125], 2, v[156:157]
	v_pk_mul_f32 v[152:153], v[128:129], v[148:149] op_sel_hi:[1,0]
	v_pk_mul_f32 v[128:129], v[126:127], v[148:149] op_sel_hi:[1,0]
	v_pk_mul_f32 v[126:127], v[122:123], v[148:149] op_sel_hi:[1,0]
	v_lshrrev_b32_e32 v0, 1, v0
	v_lshl_add_u64 v[122:123], s[40:41], 0, v[124:125]
	v_lshl_add_u64 v[124:125], s[42:43], 0, v[124:125]
	s_and_saveexec_b64 s[0:1], vcc
	s_cbranch_execz .LBB0_665
	v_lshlrev_b64 v[162:163], 2, v[0:1]
	v_lshl_add_u64 v[156:157], v[122:123], 0, v[162:163]
	v_lshl_add_u64 v[162:163], v[124:125], 0, v[162:163]
	flat_load_dwordx4 v[156:159], v[156:157]
	s_nop 0
	flat_load_dwordx4 v[162:165], v[162:163]
	s_waitcnt vmcnt(0) lgkmcnt(0)
	v_pk_mul_f32 v[168:169], v[128:129], v[156:157]
	v_pk_mul_f32 v[166:167], v[128:129], v[162:163] op_sel:[1,0] op_sel_hi:[0,0]
	v_pk_fma_f32 v[128:129], v[128:129], v[156:157], v[166:167] op_sel_hi:[1,0,1]
	v_mov_b32_e32 v162, v157
	v_mul_f32_e32 v128, v153, v163
	v_pk_fma_f32 v[170:171], v[152:153], v[162:163], v[128:129] op_sel_hi:[1,1,0] neg_lo:[0,0,1] neg_hi:[0,0,1]
	v_mov_b32_e32 v156, v163
	v_mul_f32_e32 v128, v153, v157
	v_pk_fma_f32 v[156:157], v[152:153], v[156:157], v[128:129] op_sel_hi:[1,1,0]
	v_pk_mul_f32 v[152:153], v[126:127], v[164:165] op_sel:[1,0] op_sel_hi:[0,0]
	v_pk_mul_f32 v[162:163], v[126:127], v[158:159]
	v_pk_fma_f32 v[126:127], v[126:127], v[158:159], v[152:153] op_sel_hi:[1,0,1]
	v_mov_b32_e32 v164, v159
	v_mul_f32_e32 v126, v151, v165
	v_pk_fma_f32 v[172:173], v[150:151], v[164:165], v[126:127] op_sel_hi:[1,1,0] neg_lo:[0,0,1] neg_hi:[0,0,1]
	v_mov_b32_e32 v158, v165
	v_mul_f32_e32 v126, v151, v159
	v_pk_fma_f32 v[158:159], v[150:151], v[158:159], v[126:127] op_sel_hi:[1,1,0]
	v_sub_f32_e32 v126, v162, v152
	v_sub_f32_e32 v128, v168, v166
	v_mov_b32_e32 v150, v172
	v_mov_b32_e32 v151, v158
	v_mov_b32_e32 v152, v170
	v_mov_b32_e32 v153, v156

; __device__ __forceinline__ unsigned pk4_fp8(float a, float b, float c, float d) { int w = 0; w = __builtin_amdgcn_cvt_pk_fp8_f32(a, b, w, false); w = __builtin_amdgcn_cvt_pk_fp8_f32(c, d, w, true); return (unsigned)w; }
;     __device__ __forceinline__ void operator()(const AccT& acc, const Unit& u, int wr, int wc, int fr, int fq) const {
; #pragma unroll
;         for (int ai = 0; ai < 2; ++ai)
; #pragma unroll
;             for (int m = 0; m < 4; ++m) {
;                 const int row = EPI_ROW(u, ai, m);
;                 const float r = __builtin_amdgcn_rsqf(ssq_q[row] * (1.0f / 256.0f) + RMS_EPS);
;                 const int pos = posof(row);
; #pragma unroll
;                 for (int bj = 0; bj < 2; ++bj) {
;                     const int col = EPI_COL(u, bj), d = col % 192;
;                     f32x4 v0 = acc[ai][bj][m][0] * r, v1 = acc[ai][bj][m][1] * r;
;                     if (d >= 128) { const int j0 = (d - 128) >> 1;
;                         const f32x4 c4 = *(const f32x4*)(cosT + pos * 32 + j0), s4 = *(const f32x4*)(sinT + pos * 32 + j0);
;                         rope8(v0, v1, c4, s4); }
;                     u32x2 w; w.x = pk4_fp8(v0[0], v0[1], v0[2], v0[3]); w.y = pk4_fp8(v1[0], v1[1], v1[2], v1[3]);
;                     *(u32x2*)(Q + (size_t)row * LDQ + col) = w;
;                 }
.LBB0_667:
	s_or_b64 exec, exec, s[0:1]
	v_mov_b32_e32 v122, v1
	v_mov_b32_e32 v123, v1
	v_cvt_pk_fp8_f32 v122, v118, v119
	v_cvt_pk_fp8_f32 v123, v116, v117
	v_or_b32_e32 v115, 16, v144
	v_lshlrev_b32_e32 v116, 5, v115
	v_cvt_pk_fp8_f32 v122, v128, v129 op_sel:[0,0,1]
	v_cvt_pk_fp8_f32 v123, v120, v121 op_sel:[0,0,1]
	v_and_b32_e32 v118, 0x1fbe0, v116
	v_cmp_gt_i32_e64 s[0:1], s63, v115
	flat_store_dwordx2 v[126:127], v[122:123] offset:128
	v_cndmask_b32_e64 v116, v118, v116, s[0:1]
	v_fmamk_f32 v117, v245, 0x3b800000, v236
	v_rsq_f32_e32 v118, v117
	v_ashrrev_i32_e32 v117, 31, v116
	v_lshlrev_b64 v[122:123], 2, v[116:117]
	v_lshl_add_u64 v[116:117], s[40:41], 0, v[122:123]
	v_pk_mul_f32 v[120:121], v[112:113], v[118:119] op_sel_hi:[1,0]
	v_pk_mul_f32 v[110:111], v[110:111], v[118:119] op_sel_hi:[1,0]
	v_pk_mul_f32 v[112:113], v[108:109], v[118:119] op_sel_hi:[1,0]
	v_pk_mul_f32 v[108:109], v[106:107], v[118:119] op_sel_hi:[1,0]
	v_lshl_add_u64 v[106:107], s[42:43], 0, v[122:123]
	s_and_saveexec_b64 s[0:1], vcc
	s_cbranch_execz .LBB0_669
	v_lshlrev_b64 v[126:127], 2, v[0:1]
	v_lshl_add_u64 v[122:123], v[116:117], 0, v[126:127]
	v_lshl_add_u64 v[126:127], v[106:107], 0, v[126:127]
	flat_load_dwordx4 v[122:125], v[122:123]
	s_nop 0
	flat_load_dwordx4 v[126:129], v[126:127]
	s_waitcnt vmcnt(0) lgkmcnt(0)
	v_pk_mul_f32 v[150:151], v[110:111], v[122:123]
	v_pk_mul_f32 v[148:149], v[110:111], v[126:127] op_sel:[1,0] op_sel_hi:[0,0]
	v_pk_fma_f32 v[110:111], v[110:111], v[122:123], v[148:149] op_sel_hi:[1,0,1]
	v_mov_b32_e32 v126, v123
	v_mul_f32_e32 v110, v121, v127
	v_pk_fma_f32 v[152:153], v[120:121], v[126:127], v[110:111] op_sel_hi:[1,1,0] neg_lo:[0,0,1] neg_hi:[0,0,1]
	v_mov_b32_e32 v122, v127
	v_mul_f32_e32 v110, v121, v123
	v_pk_fma_f32 v[122:123], v[120:121], v[122:123], v[110:111] op_sel_hi:[1,1,0]
	v_pk_mul_f32 v[120:121], v[108:109], v[128:129] op_sel:[1,0] op_sel_hi:[0,0]
	v_pk_mul_f32 v[126:127], v[108:109], v[124:125]
	v_pk_fma_f32 v[108:109], v[108:109], v[124:125], v[120:121] op_sel_hi:[1,0,1]
	v_mov_b32_e32 v128, v125
	v_mul_f32_e32 v108, v113, v129
	v_pk_fma_f32 v[156:157], v[112:113], v[128:129], v[108:109] op_sel_hi:[1,1,0] neg_lo:[0,0,1] neg_hi:[0,0,1]
	v_mov_b32_e32 v124, v129
	v_mul_f32_e32 v108, v113, v125
	v_pk_fma_f32 v[124:125], v[112:113], v[124:125], v[108:109] op_sel_hi:[1,1,0]
	v_sub_f32_e32 v108, v126, v120
	v_sub_f32_e32 v110, v150, v148
	v_mov_b32_e32 v112, v156
	v_mov_b32_e32 v113, v124
	v_mov_b32_e32 v120, v152
	v_mov_b32_e32 v121, v122

; __device__ __forceinline__ unsigned pk4_fp8(float a, float b, float c, float d) { int w = 0; w = __builtin_amdgcn_cvt_pk_fp8_f32(a, b, w, false); w = __builtin_amdgcn_cvt_pk_fp8_f32(c, d, w, true); return (unsigned)w; }
;     __device__ __forceinline__ void operator()(const AccT& acc, const Unit& u, int wr, int wc, int fr, int fq) const {
; #pragma unroll
;         for (int ai = 0; ai < 2; ++ai)
; #pragma unroll
;             for (int m = 0; m < 4; ++m) {
;                 const int row = EPI_ROW(u, ai, m);
;                 const float r = __builtin_amdgcn_rsqf(ssq_q[row] * (1.0f / 256.0f) + RMS_EPS);
;                 const int pos = posof(row);
; #pragma unroll
;                 for (int bj = 0; bj < 2; ++bj) {
;                     const int col = EPI_COL(u, bj), d = col % 192;
;                     f32x4 v0 = acc[ai][bj][m][0] * r, v1 = acc[ai][bj][m][1] * r;
;                     if (d >= 128) { const int j0 = (d - 128) >> 1;
;                         const f32x4 c4 = *(const f32x4*)(cosT + pos * 32 + j0), s4 = *(const f32x4*)(sinT + pos * 32 + j0);
;                         rope8(v0, v1, c4, s4); }
;                     u32x2 w; w.x = pk4_fp8(v0[0], v0[1], v0[2], v0[3]); w.y = pk4_fp8(v1[0], v1[1], v1[2], v1[3]);
;                     *(u32x2*)(Q + (size_t)row * LDQ + col) = w;
;                 }
.LBB0_671:
	s_or_b64 exec, exec, s[0:1]
	v_mov_b32_e32 v106, v1
	v_mov_b32_e32 v107, v1
	v_cvt_pk_fp8_f32 v106, v102, v103
	v_cvt_pk_fp8_f32 v107, v98, v99
	v_cvt_pk_fp8_f32 v106, v104, v105 op_sel:[0,0,1]
	v_cvt_pk_fp8_f32 v107, v100, v101 op_sel:[0,0,1]
	v_or_b32_e32 v104, 32, v144
	v_lshlrev_b32_e32 v98, 5, v104
	v_and_b32_e32 v100, 0x1fde0, v98
	flat_store_dwordx2 v[108:109], v[106:107] offset:128
	v_cmp_gt_i32_e64 s[0:1], s63, v104
	v_fmamk_f32 v99, v246, 0x3b800000, v236
	v_cndmask_b32_e64 v98, v100, v98, s[0:1]
	v_rsq_f32_e32 v100, v99
	v_ashrrev_i32_e32 v99, 31, v98
	v_lshlrev_b64 v[106:107], 2, v[98:99]
	v_lshl_add_u64 v[98:99], s[40:41], 0, v[106:107]
	v_pk_mul_f32 v[102:103], v[96:97], v[100:101] op_sel_hi:[1,0]
	v_pk_mul_f32 v[94:95], v[94:95], v[100:101] op_sel_hi:[1,0]
	v_pk_mul_f32 v[96:97], v[92:93], v[100:101] op_sel_hi:[1,0]
	v_pk_mul_f32 v[92:93], v[90:91], v[100:101] op_sel_hi:[1,0]
	v_lshl_add_u64 v[90:91], s[42:43], 0, v[106:107]
	s_and_saveexec_b64 s[0:1], vcc
	s_cbranch_execz .LBB0_673
	v_lshlrev_b64 v[110:111], 2, v[0:1]
	v_lshl_add_u64 v[106:107], v[98:99], 0, v[110:111]
	v_lshl_add_u64 v[110:111], v[90:91], 0, v[110:111]
	flat_load_dwordx4 v[106:109], v[106:107]
	s_nop 0
	flat_load_dwordx4 v[110:113], v[110:111]
	s_waitcnt vmcnt(0) lgkmcnt(0)
	v_pk_mul_f32 v[118:119], v[94:95], v[106:107]
	v_pk_mul_f32 v[116:117], v[94:95], v[110:111] op_sel:[1,0] op_sel_hi:[0,0]
	v_pk_fma_f32 v[94:95], v[94:95], v[106:107], v[116:117] op_sel_hi:[1,0,1]
	v_mov_b32_e32 v110, v107
	v_mul_f32_e32 v94, v103, v111
	v_pk_fma_f32 v[120:121], v[102:103], v[110:111], v[94:95] op_sel_hi:[1,1,0] neg_lo:[0,0,1] neg_hi:[0,0,1]
	v_mov_b32_e32 v106, v111
	v_mul_f32_e32 v94, v103, v107
	v_pk_fma_f32 v[106:107], v[102:103], v[106:107], v[94:95] op_sel_hi:[1,1,0]
	v_pk_mul_f32 v[102:103], v[92:93], v[112:113] op_sel:[1,0] op_sel_hi:[0,0]
	v_pk_mul_f32 v[110:111], v[92:93], v[108:109]
	v_pk_fma_f32 v[92:93], v[92:93], v[108:109], v[102:103] op_sel_hi:[1,0,1]
	v_mov_b32_e32 v112, v109
	v_mul_f32_e32 v92, v97, v113
	v_pk_fma_f32 v[122:123], v[96:97], v[112:113], v[92:93] op_sel_hi:[1,1,0] neg_lo:[0,0,1] neg_hi:[0,0,1]
	v_mov_b32_e32 v108, v113
	v_mul_f32_e32 v92, v97, v109
	v_pk_fma_f32 v[108:109], v[96:97], v[108:109], v[92:93] op_sel_hi:[1,1,0]
	v_sub_f32_e32 v92, v110, v102
	v_sub_f32_e32 v94, v118, v116
	v_mov_b32_e32 v96, v122
	v_mov_b32_e32 v97, v108
	v_mov_b32_e32 v102, v120
	v_mov_b32_e32 v103, v106

; __device__ __forceinline__ unsigned pk4_fp8(float a, float b, float c, float d) { int w = 0; w = __builtin_amdgcn_cvt_pk_fp8_f32(a, b, w, false); w = __builtin_amdgcn_cvt_pk_fp8_f32(c, d, w, true); return (unsigned)w; }
;     __device__ __forceinline__ void operator()(const AccT& acc, const Unit& u, int wr, int wc, int fr, int fq) const {
; #pragma unroll
;         for (int ai = 0; ai < 2; ++ai)
; #pragma unroll
;             for (int m = 0; m < 4; ++m) {
;                 const int row = EPI_ROW(u, ai, m);
;                 const float r = __builtin_amdgcn_rsqf(ssq_q[row] * (1.0f / 256.0f) + RMS_EPS);
;                 const int pos = posof(row);
; #pragma unroll
;                 for (int bj = 0; bj < 2; ++bj) {
;                     const int col = EPI_COL(u, bj), d = col % 192;
;                     f32x4 v0 = acc[ai][bj][m][0] * r, v1 = acc[ai][bj][m][1] * r;
;                     if (d >= 128) { const int j0 = (d - 128) >> 1;
;                         const f32x4 c4 = *(const f32x4*)(cosT + pos * 32 + j0), s4 = *(const f32x4*)(sinT + pos * 32 + j0);
;                         rope8(v0, v1, c4, s4); }
;                     u32x2 w; w.x = pk4_fp8(v0[0], v0[1], v0[2], v0[3]); w.y = pk4_fp8(v1[0], v1[1], v1[2], v1[3]);
;                     *(u32x2*)(Q + (size_t)row * LDQ + col) = w;
;                 }
.LBB0_675:
	s_or_b64 exec, exec, s[0:1]
	v_mov_b32_e32 v90, v1
	v_mov_b32_e32 v91, v1
	v_cvt_pk_fp8_f32 v90, v86, v87
	v_cvt_pk_fp8_f32 v91, v82, v83
	v_cvt_pk_fp8_f32 v90, v88, v89 op_sel:[0,0,1]
	v_cvt_pk_fp8_f32 v91, v84, v85 op_sel:[0,0,1]
	v_or_b32_e32 v88, 48, v144
	v_lshlrev_b32_e32 v82, 5, v88
	v_and_b32_e32 v84, 0x1ffe0, v82
	flat_store_dwordx2 v[92:93], v[90:91] offset:128
	v_cmp_gt_i32_e64 s[0:1], s63, v88
	v_fmamk_f32 v83, v247, 0x3b800000, v236
	v_cndmask_b32_e64 v82, v84, v82, s[0:1]
	v_rsq_f32_e32 v84, v83
	v_ashrrev_i32_e32 v83, 31, v82
	v_lshlrev_b64 v[90:91], 2, v[82:83]
	v_lshl_add_u64 v[82:83], s[40:41], 0, v[90:91]
	v_pk_mul_f32 v[86:87], v[80:81], v[84:85] op_sel_hi:[1,0]
	v_pk_mul_f32 v[78:79], v[78:79], v[84:85] op_sel_hi:[1,0]
	v_pk_mul_f32 v[80:81], v[76:77], v[84:85] op_sel_hi:[1,0]
	v_pk_mul_f32 v[76:77], v[74:75], v[84:85] op_sel_hi:[1,0]
	v_lshl_add_u64 v[74:75], s[42:43], 0, v[90:91]
	s_and_saveexec_b64 s[0:1], vcc
	s_cbranch_execz .LBB0_677
	v_lshlrev_b64 v[94:95], 2, v[0:1]
	v_lshl_add_u64 v[90:91], v[82:83], 0, v[94:95]
	v_lshl_add_u64 v[94:95], v[74:75], 0, v[94:95]
	flat_load_dwordx4 v[90:93], v[90:91]
	s_nop 0
	flat_load_dwordx4 v[94:97], v[94:95]
	s_waitcnt vmcnt(0) lgkmcnt(0)
	v_pk_mul_f32 v[100:101], v[78:79], v[90:91]
	v_pk_mul_f32 v[98:99], v[78:79], v[94:95] op_sel:[1,0] op_sel_hi:[0,0]
	v_pk_fma_f32 v[78:79], v[78:79], v[90:91], v[98:99] op_sel_hi:[1,0,1]
	v_mov_b32_e32 v94, v91
	v_mul_f32_e32 v78, v87, v95
	v_pk_fma_f32 v[102:103], v[86:87], v[94:95], v[78:79] op_sel_hi:[1,1,0] neg_lo:[0,0,1] neg_hi:[0,0,1]
	v_mov_b32_e32 v90, v95
	v_mul_f32_e32 v78, v87, v91
	v_pk_fma_f32 v[90:91], v[86:87], v[90:91], v[78:79] op_sel_hi:[1,1,0]
	v_pk_mul_f32 v[86:87], v[76:77], v[96:97] op_sel:[1,0] op_sel_hi:[0,0]
	v_pk_mul_f32 v[94:95], v[76:77], v[92:93]
	v_pk_fma_f32 v[76:77], v[76:77], v[92:93], v[86:87] op_sel_hi:[1,0,1]
	v_mov_b32_e32 v96, v93
	v_mul_f32_e32 v76, v81, v97
	v_pk_fma_f32 v[104:105], v[80:81], v[96:97], v[76:77] op_sel_hi:[1,1,0] neg_lo:[0,0,1] neg_hi:[0,0,1]
	v_mov_b32_e32 v92, v97
	v_mul_f32_e32 v76, v81, v93
	v_pk_fma_f32 v[92:93], v[80:81], v[92:93], v[76:77] op_sel_hi:[1,1,0]
	v_sub_f32_e32 v76, v94, v86
	v_sub_f32_e32 v78, v100, v98
	v_mov_b32_e32 v80, v104
	v_mov_b32_e32 v81, v92
	v_mov_b32_e32 v86, v102
	v_mov_b32_e32 v87, v90

; __device__ __forceinline__ unsigned pk4_fp8(float a, float b, float c, float d) { int w = 0; w = __builtin_amdgcn_cvt_pk_fp8_f32(a, b, w, false); w = __builtin_amdgcn_cvt_pk_fp8_f32(c, d, w, true); return (unsigned)w; }
;     __device__ __forceinline__ void operator()(const AccT& acc, const Unit& u, int wr, int wc, int fr, int fq) const {
; #pragma unroll
;         for (int ai = 0; ai < 2; ++ai)
; #pragma unroll
;             for (int m = 0; m < 4; ++m) {
;                 const int row = EPI_ROW(u, ai, m);
;                 const float r = __builtin_amdgcn_rsqf(ssq_q[row] * (1.0f / 256.0f) + RMS_EPS);
;                 const int pos = posof(row);
; #pragma unroll
;                 for (int bj = 0; bj < 2; ++bj) {
;                     const int col = EPI_COL(u, bj), d = col % 192;
;                     f32x4 v0 = acc[ai][bj][m][0] * r, v1 = acc[ai][bj][m][1] * r;
;                     if (d >= 128) { const int j0 = (d - 128) >> 1;
;                         const f32x4 c4 = *(const f32x4*)(cosT + pos * 32 + j0), s4 = *(const f32x4*)(sinT + pos * 32 + j0);
;                         rope8(v0, v1, c4, s4); }
;                     u32x2 w; w.x = pk4_fp8(v0[0], v0[1], v0[2], v0[3]); w.y = pk4_fp8(v1[0], v1[1], v1[2], v1[3]);
;                     *(u32x2*)(Q + (size_t)row * LDQ + col) = w;
;                 }
.LBB0_679:
	s_or_b64 exec, exec, s[0:1]
	v_mov_b32_e32 v74, v1
	v_mov_b32_e32 v75, v1
	v_cvt_pk_fp8_f32 v74, v70, v71
	v_cvt_pk_fp8_f32 v75, v66, v67
	v_cvt_pk_fp8_f32 v74, v72, v73 op_sel:[0,0,1]
	v_cvt_pk_fp8_f32 v75, v68, v69 op_sel:[0,0,1]
	v_add_u32_e32 v72, 0x80, v144
	v_lshlrev_b32_e32 v66, 5, v72
	v_and_b32_e32 v68, 0x1f9e0, v66
	flat_store_dwordx2 v[76:77], v[74:75] offset:128
	v_cmp_gt_i32_e64 s[0:1], s63, v72
	v_fmamk_f32 v67, v248, 0x3b800000, v236
	v_cndmask_b32_e64 v66, v68, v66, s[0:1]
	v_rsq_f32_e32 v68, v67
	v_ashrrev_i32_e32 v67, 31, v66
	v_lshlrev_b64 v[74:75], 2, v[66:67]
	v_lshl_add_u64 v[66:67], s[40:41], 0, v[74:75]
	v_pk_mul_f32 v[70:71], v[64:65], v[68:69] op_sel_hi:[1,0]
	v_pk_mul_f32 v[62:63], v[62:63], v[68:69] op_sel_hi:[1,0]
	v_pk_mul_f32 v[64:65], v[60:61], v[68:69] op_sel_hi:[1,0]
	v_pk_mul_f32 v[60:61], v[58:59], v[68:69] op_sel_hi:[1,0]
	v_lshl_add_u64 v[58:59], s[42:43], 0, v[74:75]
	s_and_saveexec_b64 s[0:1], vcc
	s_cbranch_execz .LBB0_681
	v_lshlrev_b64 v[78:79], 2, v[0:1]
	v_lshl_add_u64 v[74:75], v[66:67], 0, v[78:79]
	v_lshl_add_u64 v[78:79], v[58:59], 0, v[78:79]
	flat_load_dwordx4 v[74:77], v[74:75]
	s_nop 0
	flat_load_dwordx4 v[78:81], v[78:79]
	s_waitcnt vmcnt(0) lgkmcnt(0)
	v_pk_mul_f32 v[84:85], v[62:63], v[74:75]
	v_pk_mul_f32 v[82:83], v[62:63], v[78:79] op_sel:[1,0] op_sel_hi:[0,0]
	v_pk_fma_f32 v[62:63], v[62:63], v[74:75], v[82:83] op_sel_hi:[1,0,1]
	v_mov_b32_e32 v78, v75
	v_mul_f32_e32 v62, v71, v79
	v_pk_fma_f32 v[86:87], v[70:71], v[78:79], v[62:63] op_sel_hi:[1,1,0] neg_lo:[0,0,1] neg_hi:[0,0,1]
	v_mov_b32_e32 v74, v79
	v_mul_f32_e32 v62, v71, v75
	v_pk_fma_f32 v[74:75], v[70:71], v[74:75], v[62:63] op_sel_hi:[1,1,0]
	v_pk_mul_f32 v[70:71], v[60:61], v[80:81] op_sel:[1,0] op_sel_hi:[0,0]
	v_pk_mul_f32 v[78:79], v[60:61], v[76:77]
	v_pk_fma_f32 v[60:61], v[60:61], v[76:77], v[70:71] op_sel_hi:[1,0,1]
	v_mov_b32_e32 v80, v77
	v_mul_f32_e32 v60, v65, v81
	v_pk_fma_f32 v[88:89], v[64:65], v[80:81], v[60:61] op_sel_hi:[1,1,0] neg_lo:[0,0,1] neg_hi:[0,0,1]
	v_mov_b32_e32 v76, v81
	v_mul_f32_e32 v60, v65, v77
	v_pk_fma_f32 v[76:77], v[64:65], v[76:77], v[60:61] op_sel_hi:[1,1,0]
	v_sub_f32_e32 v60, v78, v70
	v_sub_f32_e32 v62, v84, v82
	v_mov_b32_e32 v64, v88
	v_mov_b32_e32 v65, v76
	v_mov_b32_e32 v70, v86
	v_mov_b32_e32 v71, v74

; __device__ __forceinline__ unsigned pk4_fp8(float a, float b, float c, float d) { int w = 0; w = __builtin_amdgcn_cvt_pk_fp8_f32(a, b, w, false); w = __builtin_amdgcn_cvt_pk_fp8_f32(c, d, w, true); return (unsigned)w; }
;     __device__ __forceinline__ void operator()(const AccT& acc, const Unit& u, int wr, int wc, int fr, int fq) const {
; #pragma unroll
;         for (int ai = 0; ai < 2; ++ai)
; #pragma unroll
;             for (int m = 0; m < 4; ++m) {
;                 const int row = EPI_ROW(u, ai, m);
;                 const float r = __builtin_amdgcn_rsqf(ssq_q[row] * (1.0f / 256.0f) + RMS_EPS);
;                 const int pos = posof(row);
; #pragma unroll
;                 for (int bj = 0; bj < 2; ++bj) {
;                     const int col = EPI_COL(u, bj), d = col % 192;
;                     f32x4 v0 = acc[ai][bj][m][0] * r, v1 = acc[ai][bj][m][1] * r;
;                     if (d >= 128) { const int j0 = (d - 128) >> 1;
;                         const f32x4 c4 = *(const f32x4*)(cosT + pos * 32 + j0), s4 = *(const f32x4*)(sinT + pos * 32 + j0);
;                         rope8(v0, v1, c4, s4); }
;                     u32x2 w; w.x = pk4_fp8(v0[0], v0[1], v0[2], v0[3]); w.y = pk4_fp8(v1[0], v1[1], v1[2], v1[3]);
;                     *(u32x2*)(Q + (size_t)row * LDQ + col) = w;
;                 }
.LBB0_683:
	s_or_b64 exec, exec, s[0:1]
	v_mov_b32_e32 v58, v1
	v_mov_b32_e32 v59, v1
	v_cvt_pk_fp8_f32 v58, v54, v55
	v_cvt_pk_fp8_f32 v59, v50, v51
	v_cvt_pk_fp8_f32 v58, v56, v57 op_sel:[0,0,1]
	v_cvt_pk_fp8_f32 v59, v52, v53 op_sel:[0,0,1]
	v_add_u32_e32 v56, 0x90, v144
	v_lshlrev_b32_e32 v50, 5, v56
	v_and_b32_e32 v52, 0x1fbe0, v50
	flat_store_dwordx2 v[60:61], v[58:59] offset:128
	v_cmp_gt_i32_e64 s[0:1], s63, v56
	v_fmamk_f32 v51, v249, 0x3b800000, v236
	v_cndmask_b32_e64 v50, v52, v50, s[0:1]
	v_rsq_f32_e32 v52, v51
	v_ashrrev_i32_e32 v51, 31, v50
	v_lshlrev_b64 v[58:59], 2, v[50:51]
	v_lshl_add_u64 v[50:51], s[40:41], 0, v[58:59]
	v_pk_mul_f32 v[54:55], v[48:49], v[52:53] op_sel_hi:[1,0]
	v_pk_mul_f32 v[46:47], v[46:47], v[52:53] op_sel_hi:[1,0]
	v_pk_mul_f32 v[48:49], v[44:45], v[52:53] op_sel_hi:[1,0]
	v_pk_mul_f32 v[44:45], v[42:43], v[52:53] op_sel_hi:[1,0]
	v_lshl_add_u64 v[42:43], s[42:43], 0, v[58:59]
	s_and_saveexec_b64 s[0:1], vcc
	s_cbranch_execz .LBB0_685
	v_lshlrev_b64 v[62:63], 2, v[0:1]
	v_lshl_add_u64 v[58:59], v[50:51], 0, v[62:63]
	v_lshl_add_u64 v[62:63], v[42:43], 0, v[62:63]
	flat_load_dwordx4 v[58:61], v[58:59]
	s_nop 0
	flat_load_dwordx4 v[62:65], v[62:63]
	s_waitcnt vmcnt(0) lgkmcnt(0)
	v_pk_mul_f32 v[68:69], v[46:47], v[58:59]
	v_pk_mul_f32 v[66:67], v[46:47], v[62:63] op_sel:[1,0] op_sel_hi:[0,0]
	v_pk_fma_f32 v[46:47], v[46:47], v[58:59], v[66:67] op_sel_hi:[1,0,1]
	v_mov_b32_e32 v62, v59
	v_mul_f32_e32 v46, v55, v63
	v_pk_fma_f32 v[70:71], v[54:55], v[62:63], v[46:47] op_sel_hi:[1,1,0] neg_lo:[0,0,1] neg_hi:[0,0,1]
	v_mov_b32_e32 v58, v63
	v_mul_f32_e32 v46, v55, v59
	v_pk_fma_f32 v[58:59], v[54:55], v[58:59], v[46:47] op_sel_hi:[1,1,0]
	v_pk_mul_f32 v[54:55], v[44:45], v[64:65] op_sel:[1,0] op_sel_hi:[0,0]
	v_pk_mul_f32 v[62:63], v[44:45], v[60:61]
	v_pk_fma_f32 v[44:45], v[44:45], v[60:61], v[54:55] op_sel_hi:[1,0,1]
	v_mov_b32_e32 v64, v61
	v_mul_f32_e32 v44, v49, v65
	v_pk_fma_f32 v[72:73], v[48:49], v[64:65], v[44:45] op_sel_hi:[1,1,0] neg_lo:[0,0,1] neg_hi:[0,0,1]
	v_mov_b32_e32 v60, v65
	v_mul_f32_e32 v44, v49, v61
	v_pk_fma_f32 v[60:61], v[48:49], v[60:61], v[44:45] op_sel_hi:[1,1,0]
	v_sub_f32_e32 v44, v62, v54
	v_sub_f32_e32 v46, v68, v66
	v_mov_b32_e32 v48, v72
	v_mov_b32_e32 v49, v60
	v_mov_b32_e32 v54, v70
	v_mov_b32_e32 v55, v58

; __device__ __forceinline__ unsigned pk4_fp8(float a, float b, float c, float d) { int w = 0; w = __builtin_amdgcn_cvt_pk_fp8_f32(a, b, w, false); w = __builtin_amdgcn_cvt_pk_fp8_f32(c, d, w, true); return (unsigned)w; }
;     __device__ __forceinline__ void operator()(const AccT& acc, const Unit& u, int wr, int wc, int fr, int fq) const {
; #pragma unroll
;         for (int ai = 0; ai < 2; ++ai)
; #pragma unroll
;             for (int m = 0; m < 4; ++m) {
;                 const int row = EPI_ROW(u, ai, m);
;                 const float r = __builtin_amdgcn_rsqf(ssq_q[row] * (1.0f / 256.0f) + RMS_EPS);
;                 const int pos = posof(row);
; #pragma unroll
;                 for (int bj = 0; bj < 2; ++bj) {
;                     const int col = EPI_COL(u, bj), d = col % 192;
;                     f32x4 v0 = acc[ai][bj][m][0] * r, v1 = acc[ai][bj][m][1] * r;
;                     if (d >= 128) { const int j0 = (d - 128) >> 1;
;                         const f32x4 c4 = *(const f32x4*)(cosT + pos * 32 + j0), s4 = *(const f32x4*)(sinT + pos * 32 + j0);
;                         rope8(v0, v1, c4, s4); }
;                     u32x2 w; w.x = pk4_fp8(v0[0], v0[1], v0[2], v0[3]); w.y = pk4_fp8(v1[0], v1[1], v1[2], v1[3]);
;                     *(u32x2*)(Q + (size_t)row * LDQ + col) = w;
;                 }
.LBB0_687:
	s_or_b64 exec, exec, s[0:1]
	v_mov_b32_e32 v42, v1
	v_mov_b32_e32 v43, v1
	v_cvt_pk_fp8_f32 v42, v38, v39
	v_cvt_pk_fp8_f32 v43, v34, v35
	v_cvt_pk_fp8_f32 v42, v40, v41 op_sel:[0,0,1]
	v_cvt_pk_fp8_f32 v43, v36, v37 op_sel:[0,0,1]
	v_add_u32_e32 v40, 0xa0, v144
	v_lshlrev_b32_e32 v34, 5, v40
	v_and_b32_e32 v36, 0x1fde0, v34
	flat_store_dwordx2 v[44:45], v[42:43] offset:128
	v_cmp_gt_i32_e64 s[0:1], s63, v40
	v_fmamk_f32 v35, v250, 0x3b800000, v236
	v_cndmask_b32_e64 v34, v36, v34, s[0:1]
	v_rsq_f32_e32 v36, v35
	v_ashrrev_i32_e32 v35, 31, v34
	v_lshlrev_b64 v[42:43], 2, v[34:35]
	v_lshl_add_u64 v[34:35], s[40:41], 0, v[42:43]
	v_pk_mul_f32 v[38:39], v[32:33], v[36:37] op_sel_hi:[1,0]
	v_pk_mul_f32 v[30:31], v[30:31], v[36:37] op_sel_hi:[1,0]
	v_pk_mul_f32 v[32:33], v[28:29], v[36:37] op_sel_hi:[1,0]
	v_pk_mul_f32 v[28:29], v[26:27], v[36:37] op_sel_hi:[1,0]
	v_lshl_add_u64 v[26:27], s[42:43], 0, v[42:43]
	s_and_saveexec_b64 s[0:1], vcc
	s_cbranch_execz .LBB0_689
	v_lshlrev_b64 v[46:47], 2, v[0:1]
	v_lshl_add_u64 v[42:43], v[34:35], 0, v[46:47]
	v_lshl_add_u64 v[46:47], v[26:27], 0, v[46:47]
	flat_load_dwordx4 v[42:45], v[42:43]
	s_nop 0
	flat_load_dwordx4 v[46:49], v[46:47]
	s_waitcnt vmcnt(0) lgkmcnt(0)
	v_pk_mul_f32 v[52:53], v[30:31], v[42:43]
	v_pk_mul_f32 v[50:51], v[30:31], v[46:47] op_sel:[1,0] op_sel_hi:[0,0]
	v_pk_fma_f32 v[30:31], v[30:31], v[42:43], v[50:51] op_sel_hi:[1,0,1]
	v_mov_b32_e32 v46, v43
	v_mul_f32_e32 v30, v39, v47
	v_pk_fma_f32 v[54:55], v[38:39], v[46:47], v[30:31] op_sel_hi:[1,1,0] neg_lo:[0,0,1] neg_hi:[0,0,1]
	v_mov_b32_e32 v42, v47
	v_mul_f32_e32 v30, v39, v43
	v_pk_fma_f32 v[42:43], v[38:39], v[42:43], v[30:31] op_sel_hi:[1,1,0]
	v_pk_mul_f32 v[38:39], v[28:29], v[48:49] op_sel:[1,0] op_sel_hi:[0,0]
	v_pk_mul_f32 v[46:47], v[28:29], v[44:45]
	v_pk_fma_f32 v[28:29], v[28:29], v[44:45], v[38:39] op_sel_hi:[1,0,1]
	v_mov_b32_e32 v48, v45
	v_mul_f32_e32 v28, v33, v49
	v_pk_fma_f32 v[56:57], v[32:33], v[48:49], v[28:29] op_sel_hi:[1,1,0] neg_lo:[0,0,1] neg_hi:[0,0,1]
	v_mov_b32_e32 v44, v49
	v_mul_f32_e32 v28, v33, v45
	v_pk_fma_f32 v[44:45], v[32:33], v[44:45], v[28:29] op_sel_hi:[1,1,0]
	v_sub_f32_e32 v28, v46, v38
	v_sub_f32_e32 v30, v52, v50
	v_mov_b32_e32 v32, v56
	v_mov_b32_e32 v33, v44
	v_mov_b32_e32 v38, v54
	v_mov_b32_e32 v39, v42

; __device__ __forceinline__ unsigned pk4_fp8(float a, float b, float c, float d) { int w = 0; w = __builtin_amdgcn_cvt_pk_fp8_f32(a, b, w, false); w = __builtin_amdgcn_cvt_pk_fp8_f32(c, d, w, true); return (unsigned)w; }
;     __device__ __forceinline__ void operator()(const AccT& acc, const Unit& u, int wr, int wc, int fr, int fq) const {
; #pragma unroll
;         for (int ai = 0; ai < 2; ++ai)
; #pragma unroll
;             for (int m = 0; m < 4; ++m) {
;                 const int row = EPI_ROW(u, ai, m);
;                 const float r = __builtin_amdgcn_rsqf(ssq_q[row] * (1.0f / 256.0f) + RMS_EPS);
;                 const int pos = posof(row);
; #pragma unroll
;                 for (int bj = 0; bj < 2; ++bj) {
;                     const int col = EPI_COL(u, bj), d = col % 192;
;                     f32x4 v0 = acc[ai][bj][m][0] * r, v1 = acc[ai][bj][m][1] * r;
;                     if (d >= 128) { const int j0 = (d - 128) >> 1;
;                         const f32x4 c4 = *(const f32x4*)(cosT + pos * 32 + j0), s4 = *(const f32x4*)(sinT + pos * 32 + j0);
;                         rope8(v0, v1, c4, s4); }
;                     u32x2 w; w.x = pk4_fp8(v0[0], v0[1], v0[2], v0[3]); w.y = pk4_fp8(v1[0], v1[1], v1[2], v1[3]);
;                     *(u32x2*)(Q + (size_t)row * LDQ + col) = w;
;                 }
.LBB0_691:
	s_or_b64 exec, exec, s[0:1]
	v_mov_b32_e32 v26, v1
	v_mov_b32_e32 v27, v1
	v_cvt_pk_fp8_f32 v26, v22, v23
	v_cvt_pk_fp8_f32 v27, v18, v19
	v_cvt_pk_fp8_f32 v26, v24, v25 op_sel:[0,0,1]
	v_cvt_pk_fp8_f32 v27, v20, v21 op_sel:[0,0,1]
	v_add_u32_e32 v24, 0xb0, v144
	v_lshlrev_b32_e32 v18, 5, v24
	v_and_b32_e32 v20, 0x1ffe0, v18
	flat_store_dwordx2 v[28:29], v[26:27] offset:128
	v_cmp_gt_i32_e64 s[0:1], s63, v24
	v_fmamk_f32 v19, v251, 0x3b800000, v236
	v_cndmask_b32_e64 v18, v20, v18, s[0:1]
	v_rsq_f32_e32 v20, v19
	v_ashrrev_i32_e32 v19, 31, v18
	v_lshlrev_b64 v[26:27], 2, v[18:19]
	v_lshl_add_u64 v[18:19], s[40:41], 0, v[26:27]
	v_pk_mul_f32 v[22:23], v[16:17], v[20:21] op_sel_hi:[1,0]
	v_pk_mul_f32 v[14:15], v[14:15], v[20:21] op_sel_hi:[1,0]
	v_pk_mul_f32 v[16:17], v[12:13], v[20:21] op_sel_hi:[1,0]
	v_pk_mul_f32 v[12:13], v[10:11], v[20:21] op_sel_hi:[1,0]
	v_lshl_add_u64 v[10:11], s[42:43], 0, v[26:27]
	s_and_saveexec_b64 s[0:1], vcc
	s_cbranch_execz .LBB0_693
	v_lshlrev_b64 v[30:31], 2, v[0:1]
	v_lshl_add_u64 v[26:27], v[18:19], 0, v[30:31]
	v_lshl_add_u64 v[30:31], v[10:11], 0, v[30:31]
	flat_load_dwordx4 v[26:29], v[26:27]
	s_nop 0
	flat_load_dwordx4 v[30:33], v[30:31]
	s_waitcnt vmcnt(0) lgkmcnt(0)
	v_pk_mul_f32 v[36:37], v[14:15], v[26:27]
	v_pk_mul_f32 v[34:35], v[14:15], v[30:31] op_sel:[1,0] op_sel_hi:[0,0]
	v_mov_b32_e32 v30, v27
	v_mul_f32_e32 v0, v23, v31
	v_pk_fma_f32 v[14:15], v[14:15], v[26:27], v[34:35] op_sel_hi:[1,0,1]
	v_pk_fma_f32 v[38:39], v[22:23], v[30:31], v[0:1] op_sel_hi:[1,1,0] neg_lo:[0,0,1] neg_hi:[0,0,1]
	v_mov_b32_e32 v26, v31
	v_mul_f32_e32 v0, v23, v27
	v_pk_fma_f32 v[26:27], v[22:23], v[26:27], v[0:1] op_sel_hi:[1,1,0]
	v_pk_mul_f32 v[22:23], v[12:13], v[32:33] op_sel:[1,0] op_sel_hi:[0,0]
	v_mov_b32_e32 v32, v29
	v_mul_f32_e32 v0, v17, v33
	v_pk_mul_f32 v[30:31], v[12:13], v[28:29]
	v_pk_fma_f32 v[12:13], v[12:13], v[28:29], v[22:23] op_sel_hi:[1,0,1]
	v_pk_fma_f32 v[40:41], v[16:17], v[32:33], v[0:1] op_sel_hi:[1,1,0] neg_lo:[0,0,1] neg_hi:[0,0,1]
	v_mov_b32_e32 v28, v33
	v_mul_f32_e32 v0, v17, v29
	v_pk_fma_f32 v[28:29], v[16:17], v[28:29], v[0:1] op_sel_hi:[1,1,0]
	v_sub_f32_e32 v12, v30, v22
	v_sub_f32_e32 v14, v36, v34
	v_mov_b32_e32 v16, v40
	v_mov_b32_e32 v17, v28
	v_mov_b32_e32 v22, v38
	v_mov_b32_e32 v23, v26
